# grid barriers: non-leader workgroups invalidate their L1 before spinning on the XCD release word instead of after it (the CU is idle meanwhile, polls bypass L1)
# speedup vs baseline: 1.0218x; 1.0003x over previous
; __device__ __forceinline__ unsigned xb_ld(unsigned* p)              { return __hip_atomic_load(p, __ATOMIC_RELAXED, __HIP_MEMORY_SCOPE_AGENT); }
; __device__ __forceinline__ unsigned xb_add(unsigned* p, unsigned v) { return __hip_atomic_fetch_add(p, v, __ATOMIC_RELAXED, __HIP_MEMORY_SCOPE_AGENT); }
; #define XB_SPIN(cond, bar) do { unsigned _sp = 0; while (cond) { __builtin_amdgcn_s_sleep(1); \
;     if ((++_sp & 255u) == 0u) { if (xb_ld(&(bar)[XB_TMO])) break; if (_sp > XB_SPIN_CAP) { atomicAdd(&(bar)[XB_TMO], 1u); break; } } } } while (0)
; __device__ __forceinline__ void xcd_barrier(const XcdBarrier& b) {
;     ...
;         const unsigned old = xb_add(&bar[XB_XSUB(b.x)], 1u);
;         const unsigned gen = old / nloc;
;         if (old + 1u == (gen + 1u) * nloc) {
;             __builtin_amdgcn_fence(__ATOMIC_RELEASE, "agent");
;             asm volatile("s_waitcnt vmcnt(0)" ::: "memory");
;             const unsigned og = xb_add(&bar[XB_TOP], 1u);
;             const unsigned tg = og / nx;
;             if (og + 1u == (tg + 1u) * nx) xb_add(&bar[XB_TOPGEN], 1u);
;             else XB_SPIN(xb_ld(&bar[XB_TOPGEN]) == tg, bar);
;             __builtin_amdgcn_fence(__ATOMIC_ACQUIRE, "agent");
;             xb_add(&bar[XB_XGEN(b.x)], 1u);
;             asm volatile("s_waitcnt vmcnt(0)" ::: "memory");
;         } else {
;             XB_SPIN(xb_ld(&bar[XB_XGEN(b.x)]) == gen, bar);
.LBB0_55:
	s_or_b64 exec, exec, s[8:9]
	v_cvt_f32_u32_e32 v5, v3
	s_waitcnt vmcnt(0)
	v_readfirstlane_b32 s0, v4
	v_sub_u32_e32 v4, 0, v3
	v_rcp_iflag_f32_e32 v5, v5
	v_add_u32_e32 v6, s0, v2
	v_mul_f32_e32 v5, 0x4f7ffffe, v5
	v_cvt_u32_f32_e32 v5, v5
	v_mul_lo_u32 v2, v4, v5
	v_mul_hi_u32 v2, v5, v2
	v_add_u32_e32 v2, v5, v2
	v_mul_hi_u32 v2, v6, v2
	v_mul_lo_u32 v4, v2, v3
	v_sub_u32_e32 v4, v6, v4
	v_add_u32_e32 v5, 1, v2
	v_cmp_ge_u32_e32 vcc, v4, v3
	s_nop 1
	v_cndmask_b32_e32 v2, v2, v5, vcc
	v_sub_u32_e32 v5, v4, v3
	v_cndmask_b32_e32 v4, v4, v5, vcc
	v_add_u32_e32 v5, 1, v2
	v_cmp_ge_u32_e32 vcc, v4, v3
	v_add_u32_e32 v4, 1, v6
	s_nop 0
	v_cndmask_b32_e32 v2, v2, v5, vcc
	v_mul_lo_u32 v5, v3, v2
	v_add_u32_e32 v3, v5, v3
	v_cmp_ne_u32_e32 vcc, v4, v3
	s_and_saveexec_b64 s[0:1], vcc
	s_xor_b64 s[6:7], exec, s[0:1]
	s_cbranch_execz .LBB0_69
	s_waitcnt lgkmcnt(0)
	v_mov_b32_e32 v1, 0x2000
	buffer_inv sc1
	global_load_dword v1, v1, s[4:5] offset:1024 sc1
	s_add_u32 s12, s4, 0x2400
	s_addc_u32 s13, s5, 0
	s_waitcnt vmcnt(0)
	v_cmp_eq_u32_e32 vcc, v1, v2
	s_and_saveexec_b64 s[8:9], vcc
	s_cbranch_execz .LBB0_68
	s_add_u32 s10, s94, 0x4200
	s_addc_u32 s11, s95, 0
	s_mov_b32 s0, 1
	s_mov_b64 s[14:15], 0
	v_mov_b32_e32 v1, 0
	s_branch .LBB0_59

; __device__ __forceinline__ unsigned xb_ld(unsigned* p)              { return __hip_atomic_load(p, __ATOMIC_RELAXED, __HIP_MEMORY_SCOPE_AGENT); }
; #define XB_SPIN(cond, bar) do { unsigned _sp = 0; while (cond) { __builtin_amdgcn_s_sleep(1); \
;     if ((++_sp & 255u) == 0u) { if (xb_ld(&(bar)[XB_TMO])) break; if (_sp > XB_SPIN_CAP) { atomicAdd(&(bar)[XB_TMO], 1u); break; } } } } while (0)
; __device__ __forceinline__ void xcd_barrier(const XcdBarrier& b) {
;     ...
;             XB_SPIN(xb_ld(&bar[XB_XGEN(b.x)]) == gen, bar);
;             __builtin_amdgcn_fence(__ATOMIC_ACQUIRE, "agent");
;             asm volatile("s_waitcnt vmcnt(0)" ::: "memory");
.LBB0_68:
	s_or_b64 exec, exec, s[8:9]
	s_waitcnt vmcnt(0)
	s_waitcnt vmcnt(0)

; __device__ __forceinline__ unsigned xb_ld(unsigned* p)              { return __hip_atomic_load(p, __ATOMIC_RELAXED, __HIP_MEMORY_SCOPE_AGENT); }
; __device__ __forceinline__ unsigned xb_add(unsigned* p, unsigned v) { return __hip_atomic_fetch_add(p, v, __ATOMIC_RELAXED, __HIP_MEMORY_SCOPE_AGENT); }
; #define XB_SPIN(cond, bar) do { unsigned _sp = 0; while (cond) { __builtin_amdgcn_s_sleep(1); \
;     if ((++_sp & 255u) == 0u) { if (xb_ld(&(bar)[XB_TMO])) break; if (_sp > XB_SPIN_CAP) { atomicAdd(&(bar)[XB_TMO], 1u); break; } } } } while (0)
; __device__ __forceinline__ void xcd_barrier(const XcdBarrier& b) {
;     ...
;         const unsigned old = xb_add(&bar[XB_XSUB(b.x)], 1u);
;         const unsigned gen = old / nloc;
;         if (old + 1u == (gen + 1u) * nloc) {
;             __builtin_amdgcn_fence(__ATOMIC_RELEASE, "agent");
;             asm volatile("s_waitcnt vmcnt(0)" ::: "memory");
;             const unsigned og = xb_add(&bar[XB_TOP], 1u);
;             const unsigned tg = og / nx;
;             if (og + 1u == (tg + 1u) * nx) xb_add(&bar[XB_TOPGEN], 1u);
;             else XB_SPIN(xb_ld(&bar[XB_TOPGEN]) == tg, bar);
;             __builtin_amdgcn_fence(__ATOMIC_ACQUIRE, "agent");
;             xb_add(&bar[XB_XGEN(b.x)], 1u);
;             asm volatile("s_waitcnt vmcnt(0)" ::: "memory");
;         } else {
;             XB_SPIN(xb_ld(&bar[XB_XGEN(b.x)]) == gen, bar);
.LBB0_1113:
	s_or_b64 exec, exec, s[6:7]
	v_cvt_f32_u32_e32 v5, v3
	s_waitcnt vmcnt(0)
	v_readfirstlane_b32 s4, v4
	v_sub_u32_e32 v4, 0, v3
	v_rcp_iflag_f32_e32 v5, v5
	v_add_u32_e32 v6, s4, v2
	v_mul_f32_e32 v5, 0x4f7ffffe, v5
	v_cvt_u32_f32_e32 v5, v5
	v_mul_lo_u32 v2, v4, v5
	v_mul_hi_u32 v2, v5, v2
	v_add_u32_e32 v2, v5, v2
	v_mul_hi_u32 v2, v6, v2
	v_mul_lo_u32 v4, v2, v3
	v_sub_u32_e32 v4, v6, v4
	v_add_u32_e32 v5, 1, v2
	v_cmp_ge_u32_e32 vcc, v4, v3
	s_nop 1
	v_cndmask_b32_e32 v2, v2, v5, vcc
	v_sub_u32_e32 v5, v4, v3
	v_cndmask_b32_e32 v4, v4, v5, vcc
	v_add_u32_e32 v5, 1, v2
	v_cmp_ge_u32_e32 vcc, v4, v3
	v_add_u32_e32 v4, 1, v6
	s_nop 0
	v_cndmask_b32_e32 v2, v2, v5, vcc
	v_mul_lo_u32 v5, v3, v2
	v_add_u32_e32 v3, v5, v3
	v_cmp_ne_u32_e32 vcc, v4, v3
	s_and_saveexec_b64 s[4:5], vcc
	s_xor_b64 s[4:5], exec, s[4:5]
	s_cbranch_execz .LBB0_1127
	s_waitcnt lgkmcnt(0)
	v_mov_b32_e32 v1, 0x2000
	buffer_inv sc1
	global_load_dword v1, v1, s[0:1] offset:1024 sc1
	s_add_u32 s10, s0, 0x2400
	s_addc_u32 s11, s1, 0
	s_waitcnt vmcnt(0)
	v_cmp_eq_u32_e32 vcc, v1, v2
	s_and_saveexec_b64 s[6:7], vcc
	s_cbranch_execz .LBB0_1126
	s_add_u32 s8, s94, 0x4200
	s_addc_u32 s9, s95, 0
	s_mov_b32 s22, 1
	s_mov_b64 s[12:13], 0
	v_mov_b32_e32 v1, 0
	s_branch .LBB0_1117

; __device__ __forceinline__ unsigned xb_ld(unsigned* p)              { return __hip_atomic_load(p, __ATOMIC_RELAXED, __HIP_MEMORY_SCOPE_AGENT); }
; #define XB_SPIN(cond, bar) do { unsigned _sp = 0; while (cond) { __builtin_amdgcn_s_sleep(1); \
;     if ((++_sp & 255u) == 0u) { if (xb_ld(&(bar)[XB_TMO])) break; if (_sp > XB_SPIN_CAP) { atomicAdd(&(bar)[XB_TMO], 1u); break; } } } } while (0)
; __device__ __forceinline__ void xcd_barrier(const XcdBarrier& b) {
;     ...
;             XB_SPIN(xb_ld(&bar[XB_XGEN(b.x)]) == gen, bar);
;             __builtin_amdgcn_fence(__ATOMIC_ACQUIRE, "agent");
;             asm volatile("s_waitcnt vmcnt(0)" ::: "memory");
.LBB0_1126:
	s_or_b64 exec, exec, s[6:7]
	s_waitcnt vmcnt(0)
	s_waitcnt vmcnt(0)
